# attention tile loop: K/V LDS-DMAs use the SGPR-base + 32-bit lane-offset form, the four 64-bit VALU address adds per tile removed
# speedup vs baseline: 1.0066x; 1.0066x over previous
.LBB0_762:
	s_add_i32 s0, s37, 2
	s_lshl_b32 s0, s0, 17
	s_add_i32 s78, s0, 0xfffc0000
	s_add_u32 s0, s76, s78
	s_addc_u32 s1, s77, 0
	s_add_u32 s98, s81, s78
	s_addc_u32 s99, s82, 0
	s_add_i32 m0, s88, 0x8000
	s_nop 0
	global_load_lds_dwordx4 v176, s[0:1] nt
	s_add_i32 m0, s72, s87
	s_nop 0
	global_load_lds_dwordx4 v190, s[98:99] nt
	s_add_i32 m0, s88, 0x8400
	s_nop 0
	global_load_lds_dwordx4 v192, s[0:1] nt
	s_add_i32 m0, s72, s90
	s_nop 0
	global_load_lds_dwordx4 v194, s[98:99] nt
	s_cmp_ge_i32 s38, s84
	s_cbranch_scc1 .LBB0_758

.LBB0_786:
	s_add_i32 s0, s37, 1
	s_lshl_b32 s0, s0, 17
	s_add_i32 s78, s0, 0xfffc0000
	s_add_u32 s0, s76, s78
	s_addc_u32 s1, s77, 0
	s_add_u32 s98, s81, s78
	s_mov_b32 m0, s88
	s_addc_u32 s99, s82, 0
	global_load_lds_dwordx4 v176, s[0:1] nt
	s_mov_b32 m0, s89
	s_nop 0
	global_load_lds_dwordx4 v190, s[98:99] nt
	s_mov_b32 m0, s91
	s_nop 0
	global_load_lds_dwordx4 v192, s[0:1] nt
	s_mov_b32 m0, s92
	s_nop 0
	global_load_lds_dwordx4 v194, s[98:99] nt
	s_add_i32 s78, s38, -2
	s_cmp_ge_i32 s78, s84
	s_cbranch_scc1 .LBB0_777

.LBB0_799:
	s_lshl_b32 s0, s37, 17
	s_add_i32 s78, s0, 0xfffc0000
	s_add_u32 s0, s76, s78
	s_addc_u32 s1, s77, 0
	s_add_u32 s98, s81, s78
	s_mov_b32 m0, s93
	s_addc_u32 s99, s82, 0
	global_load_lds_dwordx4 v176, s[0:1] nt
	s_mov_b32 m0, s94
	s_nop 0
	global_load_lds_dwordx4 v190, s[98:99] nt
	s_mov_b32 m0, s95
	s_nop 0
	global_load_lds_dwordx4 v192, s[0:1] nt
	s_mov_b32 m0, s96
	s_nop 0
	global_load_lds_dwordx4 v194, s[98:99] nt
	s_add_i32 s78, s38, -4
	s_cmp_ge_i32 s78, s84
	s_cbranch_scc1 .LBB0_783
